# all four big GEMM k-loops (bf16 in-proj + three fp8): one workgroup barrier per phase instead of two
# speedup vs baseline: 1.0006x; 1.0006x over previous
.LBB0_171:
	s_add_u32 s4, s74, 0xbc00000
	s_addc_u32 s5, s75, 0
	s_and_b32 s12, s6, 3
	s_mov_b64 s[6:7], 0x80
	s_add_i32 m0, s46, 0x18000
	v_lshl_add_u64 v[8:9], v[8:9], 0, s[6:7]
	s_lshl_b32 s9, s8, 13
	s_lshl_b32 s13, s12, 12
	s_waitcnt vmcnt(2)
	v_readfirstlane_b32 s98, v0
	s_nop 3
	s_lshr_b32 s98, s98, 8
	s_barrier
	global_load_lds_dwordx4 v[8:9], off
	v_lshl_add_u64 v[6:7], v[6:7], 0, s[6:7]
	s_add_i32 m0, s46, 0x1a000
	s_add_i32 s57, s46, 0x8000
	s_add_i32 s64, s46, 0xa000
	global_load_lds_dwordx4 v[6:7], off
	v_lshl_add_u64 v[2:3], v[2:3], 0, s[6:7]
	s_mov_b32 m0, s57
	s_add_u32 s10, s24, 0x80080
	global_load_lds_dwordx4 v[2:3], off
	v_lshl_add_u64 v[2:3], v[4:5], 0, s[6:7]
	s_mov_b32 m0, s64
	s_addc_u32 s11, s25, 0
	global_load_lds_dwordx4 v[2:3], off
	s_add_i32 m0, s46, 0x1c000
	v_lshl_add_u64 v[2:3], s[10:11], 0, v[134:135]
	global_load_lds_dwordx4 v[2:3], off
	v_lshl_add_u64 v[2:3], s[10:11], 0, v[130:131]
	s_add_i32 m0, s46, 0x1e000
	v_lshlrev_b32_e32 v4, 2, v0
	global_load_lds_dwordx4 v[2:3], off
	v_and_b32_e32 v2, 15, v0
	v_lshlrev_b32_e32 v3, 1, v13
	v_lshl_or_b32 v150, s8, 6, v2
	v_lshl_or_b32 v2, v2, 6, v3
	v_and_b32_e32 v4, 32, v4
	s_sext_i32_i16 s79, s2
	v_bitop3_b32 v6, v2, s9, v4 bitop3:0xde
	v_lshlrev_b32_e32 v2, 6, v0
	s_movk_i32 s2, 0x3c0
	v_and_or_b32 v2, v2, s2, v3
	v_bitop3_b32 v151, s13, v2, v4 bitop3:0xf6
	v_mul_u32_u24_e32 v2, 0x5000, v13
	v_lshlrev_b32_e32 v2, 2, v2
	v_mov_b32_e32 v3, v135
	s_cmpk_lt_u32 s3, 0x100
	v_lshl_add_u64 v[2:3], s[74:75], 0, v[2:3]
	s_mov_b64 s[2:3], 0x200000
	v_lshl_add_u64 v[138:139], v[2:3], 0, s[2:3]
	v_lshlrev_b32_e32 v2, 9, v0
	v_and_b32_e32 v2, 0x30000, v2
	v_lshlrev_b32_e32 v3, 12, v14
	v_or3_b32 v2, v11, v2, v3
	v_add_u32_e32 v140, v2, v12
	v_lshlrev_b32_e32 v2, 5, v10
	v_and_b32_e32 v2, 0x70000, v2
	s_waitcnt vmcnt(6)
	v_or3_b32 v2, v11, v2, v3
	v_mov_b32_e32 v4, v135
	v_mov_b32_e32 v5, v135
	s_cselect_b64 s[8:9], -1, 0
	s_cmp_eq_u32 s12, 0
	v_lshl_or_b32 v152, s12, 5, v13
	v_add_u32_e32 v142, v2, v12
	v_mov_b32_e32 v2, v135
	v_mov_b32_e32 v3, v135
	v_add_u32_e32 v153, 0, v6
	v_mov_b64_e32 v[8:9], v[4:5]
	v_mov_b64_e32 v[12:13], v[4:5]
	v_mov_b64_e32 v[16:17], v[4:5]
	v_mov_b64_e32 v[20:21], v[4:5]
	v_mov_b64_e32 v[24:25], v[4:5]
	v_mov_b64_e32 v[28:29], v[4:5]
	v_mov_b64_e32 v[32:33], v[4:5]
	v_mov_b64_e32 v[36:37], v[4:5]
	v_mov_b64_e32 v[40:41], v[4:5]
	v_mov_b64_e32 v[44:45], v[4:5]
	v_mov_b64_e32 v[48:49], v[4:5]
	v_mov_b64_e32 v[52:53], v[4:5]
	v_mov_b64_e32 v[56:57], v[4:5]
	v_mov_b64_e32 v[60:61], v[4:5]
	v_mov_b64_e32 v[64:65], v[4:5]
	v_mov_b64_e32 v[68:69], v[4:5]
	v_mov_b64_e32 v[72:73], v[4:5]
	v_mov_b64_e32 v[76:77], v[4:5]
	v_mov_b64_e32 v[80:81], v[4:5]
	v_mov_b64_e32 v[84:85], v[4:5]
	v_mov_b64_e32 v[88:89], v[4:5]
	v_mov_b64_e32 v[92:93], v[4:5]
	v_mov_b64_e32 v[96:97], v[4:5]
	v_mov_b64_e32 v[100:101], v[4:5]
	v_mov_b64_e32 v[104:105], v[4:5]
	v_mov_b64_e32 v[108:109], v[4:5]
	v_mov_b64_e32 v[112:113], v[4:5]
	v_mov_b64_e32 v[116:117], v[4:5]
	v_mov_b64_e32 v[120:121], v[4:5]
	v_mov_b64_e32 v[124:125], v[4:5]
	v_mov_b64_e32 v[128:129], v[4:5]
	s_cselect_b64 s[10:11], -1, 0
	s_ashr_i32 s65, s33, 31
	v_mov_b32_e32 v141, v135
	v_mov_b32_e32 v143, v135
	v_mov_b64_e32 v[144:145], 0x690
	v_mov_b64_e32 v[146:147], 0x68f
	s_add_i32 s66, 0, 0x10000
	s_add_i32 s67, 0, 0x14000
	s_movk_i32 s78, 0x2800
	v_mov_b64_e32 v[6:7], v[2:3]
	v_mov_b64_e32 v[10:11], v[2:3]
	v_mov_b64_e32 v[14:15], v[2:3]
	v_mov_b64_e32 v[18:19], v[2:3]
	v_mov_b64_e32 v[22:23], v[2:3]
	v_mov_b64_e32 v[26:27], v[2:3]
	v_mov_b64_e32 v[30:31], v[2:3]
	v_mov_b64_e32 v[34:35], v[2:3]
	v_mov_b64_e32 v[38:39], v[2:3]
	v_mov_b64_e32 v[42:43], v[2:3]
	v_mov_b64_e32 v[46:47], v[2:3]
	v_mov_b64_e32 v[50:51], v[2:3]
	v_mov_b64_e32 v[54:55], v[2:3]
	v_mov_b64_e32 v[58:59], v[2:3]
	v_mov_b64_e32 v[62:63], v[2:3]
	v_mov_b64_e32 v[66:67], v[2:3]
	v_mov_b64_e32 v[70:71], v[2:3]
	v_mov_b64_e32 v[74:75], v[2:3]
	v_mov_b64_e32 v[78:79], v[2:3]
	v_mov_b64_e32 v[82:83], v[2:3]
	v_mov_b64_e32 v[86:87], v[2:3]
	v_mov_b64_e32 v[90:91], v[2:3]
	v_mov_b64_e32 v[94:95], v[2:3]
	v_mov_b64_e32 v[98:99], v[2:3]
	v_mov_b64_e32 v[102:103], v[2:3]
	v_mov_b64_e32 v[106:107], v[2:3]
	v_mov_b64_e32 v[110:111], v[2:3]
	v_mov_b64_e32 v[114:115], v[2:3]
	v_mov_b64_e32 v[118:119], v[2:3]
	v_mov_b64_e32 v[122:123], v[2:3]
	v_mov_b64_e32 v[126:127], v[2:3]
	s_barrier
	s_branch .LBB0_174

.LBB0_177:
	v_add_u32_e32 v148, s66, v151
	ds_read_b128 v[154:157], v148
	ds_read_b128 v[158:161], v148 offset:1024
	ds_read_b128 v[162:165], v148 offset:2048
	ds_read_b128 v[166:169], v148 offset:3072
	v_add_u32_e32 v148, s67, v151
	ds_read_b128 v[170:173], v148
	ds_read_b128 v[174:177], v148 offset:1024
	ds_read_b128 v[178:181], v148 offset:2048
	ds_read_b128 v[182:185], v148 offset:3072
	s_add_u32 s24, s22, 0xfff80080
	s_addc_u32 s25, s23, -1
	s_cmp_eq_u32 s83, 28
	s_cselect_b32 s27, s15, s25
	s_cselect_b32 s26, s21, s24
	s_cselect_b32 s25, s13, s82
	s_cselect_b32 s24, s80, s81
	v_lshl_add_u64 v[148:149], s[22:23], 0, v[140:141]
	s_add_i32 m0, s46, 0xc000
	ds_read_b128 v[186:189], v153
	ds_read_b128 v[190:193], v153 offset:1024
	ds_read_b128 v[194:197], v153 offset:2048
	ds_read_b128 v[198:201], v153 offset:3072
	ds_read_b128 v[202:205], v153 offset:4096
	ds_read_b128 v[206:209], v153 offset:5120
	ds_read_b128 v[210:213], v153 offset:6144
	ds_read_b128 v[214:217], v153 offset:7168
	global_load_lds_dwordx4 v[148:149], off
	v_lshl_add_u64 v[148:149], s[22:23], 0, v[142:143]
	s_add_i32 m0, s46, 0xe000
	s_nop 0
	global_load_lds_dwordx4 v[148:149], off
	s_waitcnt vmcnt(8)
	s_waitcnt lgkmcnt(0)
	s_cmp_lg_u32 s98, 0
	s_cbranch_scc1 .Lhb_p2_0
	s_barrier
.Lhb_p2_0:
	s_setprio 1
	s_waitcnt lgkmcnt(0)
	v_mfma_f32_16x16x32_bf16 v[126:129], v[154:157], v[186:189], v[126:129]
	v_mfma_f32_16x16x32_bf16 v[122:125], v[162:165], v[186:189], v[122:125]
	v_mfma_f32_16x16x32_bf16 v[118:121], v[154:157], v[194:197], v[118:121]
	v_mfma_f32_16x16x32_bf16 v[114:117], v[162:165], v[194:197], v[114:117]
	v_mfma_f32_16x16x32_bf16 v[110:113], v[154:157], v[202:205], v[110:113]
	v_mfma_f32_16x16x32_bf16 v[106:109], v[162:165], v[202:205], v[106:109]
	v_mfma_f32_16x16x32_bf16 v[102:105], v[154:157], v[210:213], v[102:105]
	v_mfma_f32_16x16x32_bf16 v[98:101], v[162:165], v[210:213], v[98:101]
	v_mfma_f32_16x16x32_bf16 v[126:129], v[158:161], v[190:193], v[126:129]
	v_mfma_f32_16x16x32_bf16 v[122:125], v[166:169], v[190:193], v[122:125]
	v_mfma_f32_16x16x32_bf16 v[118:121], v[158:161], v[198:201], v[118:121]
	v_mfma_f32_16x16x32_bf16 v[114:117], v[166:169], v[198:201], v[114:117]
	v_mfma_f32_16x16x32_bf16 v[110:113], v[158:161], v[206:209], v[110:113]
	v_mfma_f32_16x16x32_bf16 v[106:109], v[166:169], v[206:209], v[106:109]
	v_mfma_f32_16x16x32_bf16 v[102:105], v[158:161], v[214:217], v[102:105]
	v_mfma_f32_16x16x32_bf16 v[98:101], v[166:169], v[214:217], v[98:101]
	s_setprio 0
	s_setprio 1
	v_mfma_f32_16x16x32_bf16 v[94:97], v[170:173], v[186:189], v[94:97]
	v_mfma_f32_16x16x32_bf16 v[90:93], v[178:181], v[186:189], v[90:93]
	v_mfma_f32_16x16x32_bf16 v[86:89], v[170:173], v[194:197], v[86:89]
	v_mfma_f32_16x16x32_bf16 v[82:85], v[178:181], v[194:197], v[82:85]
	v_mfma_f32_16x16x32_bf16 v[78:81], v[170:173], v[202:205], v[78:81]
	v_mfma_f32_16x16x32_bf16 v[74:77], v[178:181], v[202:205], v[74:77]
	v_mfma_f32_16x16x32_bf16 v[70:73], v[170:173], v[210:213], v[70:73]
	v_mfma_f32_16x16x32_bf16 v[66:69], v[178:181], v[210:213], v[66:69]
	v_mfma_f32_16x16x32_bf16 v[94:97], v[174:177], v[190:193], v[94:97]
	v_mfma_f32_16x16x32_bf16 v[90:93], v[182:185], v[190:193], v[90:93]
	v_mfma_f32_16x16x32_bf16 v[86:89], v[174:177], v[198:201], v[86:89]
	v_mfma_f32_16x16x32_bf16 v[82:85], v[182:185], v[198:201], v[82:85]
	v_mfma_f32_16x16x32_bf16 v[78:81], v[174:177], v[206:209], v[78:81]
	v_mfma_f32_16x16x32_bf16 v[74:77], v[182:185], v[206:209], v[74:77]
	v_mfma_f32_16x16x32_bf16 v[70:73], v[174:177], v[214:217], v[70:73]
	v_mfma_f32_16x16x32_bf16 v[66:69], v[182:185], v[214:217], v[66:69]
	s_setprio 0
	s_cmp_lg_u32 s98, 1
	s_cbranch_scc1 .Lhb_p2_1
	s_barrier
.Lhb_p2_1:
	s_add_i32 s84, s66, s41
	v_lshl_add_u64 v[148:149], s[24:25], 0, v[134:135]
	s_mov_b32 m0, s84
	ds_read_b128 v[186:189], v153 offset:16384
	ds_read_b128 v[190:193], v153 offset:17408
	ds_read_b128 v[194:197], v153 offset:18432
	ds_read_b128 v[198:201], v153 offset:19456
	ds_read_b128 v[202:205], v153 offset:20480
	ds_read_b128 v[206:209], v153 offset:21504
	ds_read_b128 v[210:213], v153 offset:22528
	ds_read_b128 v[214:217], v153 offset:23552
	global_load_lds_dwordx4 v[148:149], off
	s_add_i32 m0, s84, 0x2000
	s_add_u32 s84, s24, 0x80000
	v_lshl_add_u64 v[218:219], s[24:25], 0, v[130:131]
	s_addc_u32 s85, s25, 0
	s_add_i32 s86, s67, s41
	global_load_lds_dwordx4 v[218:219], off
	v_lshl_add_u64 v[220:221], s[84:85], 0, v[134:135]
	s_mov_b32 m0, s86
	v_lshl_add_u64 v[222:223], s[26:27], 0, v[132:133]
	global_load_lds_dwordx4 v[220:221], off
	v_lshl_add_u64 v[220:221], s[84:85], 0, v[130:131]
	s_add_i32 m0, s86, 0x2000
	s_nop 0
	global_load_lds_dwordx4 v[220:221], off
	v_lshl_add_u64 v[220:221], s[26:27], 0, v[136:137]
	s_mov_b32 m0, s46
	s_nop 0
	global_load_lds_dwordx4 v[220:221], off
	s_mov_b32 m0, s47
	s_nop 0
	global_load_lds_dwordx4 v[222:223], off
	s_waitcnt vmcnt(8)
	s_waitcnt lgkmcnt(0)
	s_cmp_lg_u32 s98, 0
	s_cbranch_scc1 .Lhb_p2_2
	s_barrier
.Lhb_p2_2:
	s_setprio 1
	s_waitcnt lgkmcnt(0)
	v_mfma_f32_16x16x32_bf16 v[62:65], v[154:157], v[186:189], v[62:65]
	v_mfma_f32_16x16x32_bf16 v[58:61], v[162:165], v[186:189], v[58:61]
	v_mfma_f32_16x16x32_bf16 v[54:57], v[154:157], v[194:197], v[54:57]
	v_mfma_f32_16x16x32_bf16 v[50:53], v[162:165], v[194:197], v[50:53]
	v_mfma_f32_16x16x32_bf16 v[46:49], v[154:157], v[202:205], v[46:49]
	v_mfma_f32_16x16x32_bf16 v[42:45], v[162:165], v[202:205], v[42:45]
	v_mfma_f32_16x16x32_bf16 v[38:41], v[154:157], v[210:213], v[38:41]
	v_mfma_f32_16x16x32_bf16 v[34:37], v[162:165], v[210:213], v[34:37]
	v_mfma_f32_16x16x32_bf16 v[62:65], v[158:161], v[190:193], v[62:65]
	v_mfma_f32_16x16x32_bf16 v[58:61], v[166:169], v[190:193], v[58:61]
	v_mfma_f32_16x16x32_bf16 v[54:57], v[158:161], v[198:201], v[54:57]
	v_mfma_f32_16x16x32_bf16 v[50:53], v[166:169], v[198:201], v[50:53]
	v_mfma_f32_16x16x32_bf16 v[46:49], v[158:161], v[206:209], v[46:49]
	v_mfma_f32_16x16x32_bf16 v[42:45], v[166:169], v[206:209], v[42:45]
	v_mfma_f32_16x16x32_bf16 v[38:41], v[158:161], v[214:217], v[38:41]
	v_mfma_f32_16x16x32_bf16 v[34:37], v[166:169], v[214:217], v[34:37]
	s_setprio 0
	s_setprio 1
	v_mfma_f32_16x16x32_bf16 v[30:33], v[170:173], v[186:189], v[30:33]
	v_mfma_f32_16x16x32_bf16 v[26:29], v[178:181], v[186:189], v[26:29]
	v_mfma_f32_16x16x32_bf16 v[22:25], v[170:173], v[194:197], v[22:25]
	v_mfma_f32_16x16x32_bf16 v[18:21], v[178:181], v[194:197], v[18:21]
	v_mfma_f32_16x16x32_bf16 v[14:17], v[170:173], v[202:205], v[14:17]
	v_mfma_f32_16x16x32_bf16 v[10:13], v[178:181], v[202:205], v[10:13]
	v_mfma_f32_16x16x32_bf16 v[6:9], v[170:173], v[210:213], v[6:9]
	v_mfma_f32_16x16x32_bf16 v[2:5], v[178:181], v[210:213], v[2:5]
	v_mfma_f32_16x16x32_bf16 v[30:33], v[174:177], v[190:193], v[30:33]
	v_mfma_f32_16x16x32_bf16 v[26:29], v[182:185], v[190:193], v[26:29]
	v_mfma_f32_16x16x32_bf16 v[22:25], v[174:177], v[198:201], v[22:25]
	v_mfma_f32_16x16x32_bf16 v[18:21], v[182:185], v[198:201], v[18:21]
	v_mfma_f32_16x16x32_bf16 v[14:17], v[174:177], v[206:209], v[14:17]
	v_mfma_f32_16x16x32_bf16 v[10:13], v[182:185], v[206:209], v[10:13]
	v_mfma_f32_16x16x32_bf16 v[6:9], v[174:177], v[214:217], v[6:9]
	v_mfma_f32_16x16x32_bf16 v[2:5], v[182:185], v[214:217], v[2:5]
	s_setprio 0
	s_cmp_lg_u32 s98, 1
	s_cbranch_scc1 .Lhb_p2_3
	s_barrier
.Lhb_p2_3:
	s_add_i32 s84, 0, 0x18000
	s_add_i32 s85, 0, 0x1c000
	v_add_u32_e32 v166, s84, v151
	v_add_u32_e32 v182, s85, v151
	ds_read_b128 v[154:157], v166
	ds_read_b128 v[158:161], v166 offset:1024
	ds_read_b128 v[162:165], v166 offset:2048
	ds_read_b128 v[166:169], v166 offset:3072
	ds_read_b128 v[170:173], v182
	ds_read_b128 v[174:177], v182 offset:1024
	ds_read_b128 v[178:181], v182 offset:2048
	ds_read_b128 v[182:185], v182 offset:3072
	s_add_u32 s26, s26, 0x80000
	s_addc_u32 s27, s27, 0
	s_mov_b32 m0, s48
	v_lshl_add_u64 v[224:225], s[26:27], 0, v[136:137]
	ds_read_b128 v[186:189], v153 offset:32768
	ds_read_b128 v[190:193], v153 offset:33792
	ds_read_b128 v[194:197], v153 offset:34816
	ds_read_b128 v[198:201], v153 offset:35840
	ds_read_b128 v[202:205], v153 offset:36864
	ds_read_b128 v[206:209], v153 offset:37888
	ds_read_b128 v[210:213], v153 offset:38912
	ds_read_b128 v[214:217], v153 offset:39936
	global_load_lds_dwordx4 v[224:225], off
	v_lshl_add_u64 v[224:225], s[26:27], 0, v[132:133]
	s_mov_b32 m0, s49
	s_nop 0
	global_load_lds_dwordx4 v[224:225], off
	s_waitcnt vmcnt(8)
	s_waitcnt lgkmcnt(0)
	s_cmp_lg_u32 s98, 0
	s_cbranch_scc1 .Lhb_p2_4
	s_barrier

.Lhb_p2_5:
	s_add_i32 s26, s84, s41
	v_lshl_add_u64 v[148:149], v[148:149], 0, s[6:7]
	s_mov_b32 m0, s26
	ds_read_b128 v[186:189], v153 offset:49152
	ds_read_b128 v[190:193], v153 offset:50176
	ds_read_b128 v[194:197], v153 offset:51200
	ds_read_b128 v[198:201], v153 offset:52224
	ds_read_b128 v[202:205], v153 offset:53248
	ds_read_b128 v[206:209], v153 offset:54272
	ds_read_b128 v[210:213], v153 offset:55296
	ds_read_b128 v[214:217], v153 offset:56320
	global_load_lds_dwordx4 v[148:149], off
	s_add_i32 m0, s26, 0x2000
	s_add_u32 s24, s24, 0x80080
	v_lshl_add_u64 v[148:149], v[218:219], 0, s[6:7]
	s_addc_u32 s25, s25, 0
	s_add_i32 s26, s85, s41
	global_load_lds_dwordx4 v[148:149], off
	v_lshl_add_u64 v[148:149], s[24:25], 0, v[134:135]
	s_mov_b32 m0, s26
	s_nop 0
	global_load_lds_dwordx4 v[148:149], off
	v_lshl_add_u64 v[148:149], s[24:25], 0, v[130:131]
	s_add_i32 m0, s26, 0x2000
	s_nop 0
	global_load_lds_dwordx4 v[148:149], off
	v_lshl_add_u64 v[148:149], v[220:221], 0, s[6:7]
	s_mov_b32 m0, s57
	s_nop 0
	global_load_lds_dwordx4 v[148:149], off
	v_lshl_add_u64 v[148:149], v[222:223], 0, s[6:7]
	s_mov_b32 m0, s64
	s_nop 0
	global_load_lds_dwordx4 v[148:149], off
	s_waitcnt vmcnt(8)
	s_waitcnt lgkmcnt(0)
	s_cmp_lg_u32 s98, 0
	s_cbranch_scc1 .Lhb_p2_6
	s_barrier

.Lhb_p2_7:
	s_add_i32 s83, s83, 2
	s_add_u32 s22, s22, 0x100
	s_addc_u32 s23, s23, 0
	s_add_u32 s81, s81, 0x100
	s_addc_u32 s82, s82, 0
	s_cmp_gt_u32 s83, 29
	s_cbranch_scc0 .LBB0_177
	s_and_b64 vcc, exec, s[8:9]
	s_cbranch_vccz .LBB0_182
	v_lshl_add_u32 v148, s20, 8, v150
	s_cmp_gt_i32 s79, 19
	s_mov_b64 s[20:21], -1
	s_cbranch_scc1 .LBB0_183

.LBB0_186:
	s_andn2_b64 vcc, exec, s[0:1]
	s_cbranch_vccnz .LBB0_172
	s_branch .LBB0_172

.LBB0_583:
	s_add_u32 s4, s74, 0x18400000
	s_addc_u32 s5, s75, 0
	s_add_u32 s6, s74, 0x1d400000
	s_addc_u32 s7, s75, 0
	s_lshl_b32 s8, s8, 5
	s_and_b32 s14, s8, 0x60
	s_mov_b64 s[8:9], 0x80
	s_add_i32 m0, s17, 0x18000
	v_lshl_add_u64 v[8:9], v[8:9], 0, s[8:9]
	s_lshl_b32 s11, s3, 13
	s_lshl_b32 s15, s14, 7
	s_waitcnt vmcnt(2)
	v_readfirstlane_b32 s98, v0
	s_nop 3
	s_lshr_b32 s98, s98, 8
	s_barrier
	global_load_lds_dwordx4 v[8:9], off
	v_lshl_add_u64 v[6:7], v[6:7], 0, s[8:9]
	s_add_i32 m0, s17, 0x1a000
	s_add_i32 s43, s17, 0x8000
	s_add_i32 s44, s17, 0xa000
	global_load_lds_dwordx4 v[6:7], off
	v_lshl_add_u64 v[2:3], v[2:3], 0, s[8:9]
	s_mov_b32 m0, s43
	s_add_u32 s12, s24, 0x40080
	global_load_lds_dwordx4 v[2:3], off
	v_lshl_add_u64 v[2:3], v[4:5], 0, s[8:9]
	s_mov_b32 m0, s44
	s_addc_u32 s13, s25, 0
	global_load_lds_dwordx4 v[2:3], off
	s_add_i32 m0, s17, 0x1c000
	v_lshl_add_u64 v[2:3], s[12:13], 0, v[156:157]
	global_load_lds_dwordx4 v[2:3], off
	v_lshl_add_u64 v[2:3], s[12:13], 0, v[160:161]
	s_add_i32 m0, s17, 0x1e000
	s_sext_i32_i8 s67, s2
	global_load_lds_dwordx4 v[2:3], off
	v_and_b32_e32 v2, 15, v0
	v_lshlrev_b32_e32 v3, 1, v13
	v_lshlrev_b32_e32 v4, 2, v0
	v_lshlrev_b32_e32 v5, 6, v0
	s_movk_i32 s2, 0x3c0
	v_lshl_or_b32 v1, s3, 6, v2
	v_lshl_or_b32 v2, v2, 6, v3
	v_and_b32_e32 v4, 32, v4
	v_and_or_b32 v3, v5, s2, v3
	v_bitop3_b32 v178, s15, v3, v4 bitop3:0xf6
	v_lshlrev_b32_e32 v3, 8, v0
	v_bitop3_b32 v2, v2, s11, v4 bitop3:0xde
	v_and_b32_e32 v3, 0x18000, v3
	v_lshlrev_b32_e32 v4, 11, v12
	v_or3_b32 v3, v10, v3, v4
	v_add_u32_e32 v162, v3, v11
	v_lshlrev_b32_e32 v3, 4, v14
	s_waitcnt vmcnt(6)
	v_and_b32_e32 v3, 0x38000, v3
	v_mov_b32_e32 v28, v157
	v_mov_b32_e32 v29, v157
	s_cmpk_lt_u32 s10, 0x100
	v_or3_b32 v3, v10, v3, v4
	v_mov_b32_e32 v26, v157
	v_mov_b32_e32 v27, v157
	v_mov_b64_e32 v[32:33], v[28:29]
	v_mov_b64_e32 v[36:37], v[28:29]
	v_mov_b64_e32 v[40:41], v[28:29]
	v_mov_b64_e32 v[44:45], v[28:29]
	v_mov_b64_e32 v[48:49], v[28:29]
	v_mov_b64_e32 v[52:53], v[28:29]
	v_mov_b64_e32 v[56:57], v[28:29]
	v_mov_b64_e32 v[60:61], v[28:29]
	v_mov_b64_e32 v[64:65], v[28:29]
	v_mov_b64_e32 v[68:69], v[28:29]
	v_mov_b64_e32 v[72:73], v[28:29]
	v_mov_b64_e32 v[76:77], v[28:29]
	v_mov_b64_e32 v[80:81], v[28:29]
	v_mov_b64_e32 v[84:85], v[28:29]
	v_mov_b64_e32 v[88:89], v[28:29]
	v_mov_b64_e32 v[92:93], v[28:29]
	v_mov_b64_e32 v[96:97], v[28:29]
	v_mov_b64_e32 v[100:101], v[28:29]
	v_mov_b64_e32 v[104:105], v[28:29]
	v_mov_b64_e32 v[108:109], v[28:29]
	v_mov_b64_e32 v[112:113], v[28:29]
	v_mov_b64_e32 v[116:117], v[28:29]
	v_mov_b64_e32 v[120:121], v[28:29]
	v_mov_b64_e32 v[124:125], v[28:29]
	v_mov_b64_e32 v[128:129], v[28:29]
	v_mov_b64_e32 v[132:133], v[28:29]
	v_mov_b64_e32 v[136:137], v[28:29]
	v_mov_b64_e32 v[140:141], v[28:29]
	v_mov_b64_e32 v[144:145], v[28:29]
	v_mov_b64_e32 v[148:149], v[28:29]
	v_mov_b64_e32 v[152:153], v[28:29]
	s_cselect_b64 s[10:11], -1, 0
	s_ashr_i32 s45, s33, 31
	s_ashr_i32 s46, s30, 31
	v_add_u32_e32 v179, 0xffffc000, v1
	v_or_b32_e32 v180, s14, v13
	v_mov_b32_e32 v163, v157
	v_add_u32_e32 v164, v3, v11
	v_mov_b32_e32 v165, v157
	s_mov_b32 s47, 0
	s_add_i32 s48, 0, 0x10000
	s_add_i32 s49, 0, 0x14000
	v_add_u32_e32 v181, 0, v2
	v_mov_b32_e32 v182, 0x7a7a7a7a
	s_mov_b32 s56, 0x20000
	s_mov_b32 s57, 0x30000
	s_mov_b32 s58, 0x80000
	s_mov_b32 s59, 0x90000
	s_mov_b32 s60, 0xa0000
	s_mov_b32 s61, 0xb0000
	v_mov_b64_e32 v[166:167], 0xff
	v_mov_b64_e32 v[168:169], 0x1ff
	v_mov_b64_e32 v[30:31], v[26:27]
	v_mov_b64_e32 v[34:35], v[26:27]
	v_mov_b64_e32 v[38:39], v[26:27]
	v_mov_b64_e32 v[42:43], v[26:27]
	v_mov_b64_e32 v[46:47], v[26:27]
	v_mov_b64_e32 v[50:51], v[26:27]
	v_mov_b64_e32 v[54:55], v[26:27]
	v_mov_b64_e32 v[58:59], v[26:27]
	v_mov_b64_e32 v[62:63], v[26:27]
	v_mov_b64_e32 v[66:67], v[26:27]
	v_mov_b64_e32 v[70:71], v[26:27]
	v_mov_b64_e32 v[74:75], v[26:27]
	v_mov_b64_e32 v[78:79], v[26:27]
	v_mov_b64_e32 v[82:83], v[26:27]
	v_mov_b64_e32 v[86:87], v[26:27]
	v_mov_b64_e32 v[90:91], v[26:27]
	v_mov_b64_e32 v[94:95], v[26:27]
	v_mov_b64_e32 v[98:99], v[26:27]
	v_mov_b64_e32 v[102:103], v[26:27]
	v_mov_b64_e32 v[106:107], v[26:27]
	v_mov_b64_e32 v[110:111], v[26:27]
	v_mov_b64_e32 v[114:115], v[26:27]
	v_mov_b64_e32 v[118:119], v[26:27]
	v_mov_b64_e32 v[122:123], v[26:27]
	v_mov_b64_e32 v[126:127], v[26:27]
	v_mov_b64_e32 v[130:131], v[26:27]
	v_mov_b64_e32 v[134:135], v[26:27]
	v_mov_b64_e32 v[138:139], v[26:27]
	v_mov_b64_e32 v[142:143], v[26:27]
	v_mov_b64_e32 v[146:147], v[26:27]
	v_mov_b64_e32 v[150:151], v[26:27]
	s_barrier
	s_branch .LBB0_586

.LBB0_603:
	v_add_u32_e32 v14, s48, v178
	v_add_u32_e32 v170, s49, v178
	ds_read_b128 v[2:5], v14
	ds_read_b128 v[6:9], v14 offset:1024
	ds_read_b128 v[10:13], v14 offset:2048
	ds_read_b128 v[14:17], v14 offset:3072
	ds_read_b128 v[18:21], v170
	ds_read_b128 v[22:25], v170 offset:1024
	ds_read_b128 v[184:187], v170 offset:2048
	ds_read_b128 v[188:191], v170 offset:3072
	s_add_i32 s69, s24, 2
	s_add_u32 s25, s22, 0xfffc0080
	s_addc_u32 s26, s23, -1
	s_cmp_eq_u32 s13, s24
	s_cselect_b32 s24, s20, s15
	s_cselect_b32 s27, s19, s26
	s_cselect_b32 s26, s18, s25
	s_cselect_b32 s25, s21, s68
	v_lshl_add_u64 v[216:217], s[22:23], 0, v[162:163]
	s_add_i32 m0, s17, 0xc000
	ds_read_b128 v[170:173], v181
	ds_read_b128 v[174:177], v181 offset:1024
	ds_read_b128 v[192:195], v181 offset:2048
	ds_read_b128 v[196:199], v181 offset:3072
	ds_read_b128 v[200:203], v181 offset:4096
	ds_read_b128 v[204:207], v181 offset:5120
	ds_read_b128 v[208:211], v181 offset:6144
	ds_read_b128 v[212:215], v181 offset:7168
	global_load_lds_dwordx4 v[216:217], off
	v_lshl_add_u64 v[216:217], s[22:23], 0, v[164:165]
	s_add_i32 m0, s17, 0xe000
	s_nop 0
	global_load_lds_dwordx4 v[216:217], off
	s_waitcnt vmcnt(8)
	s_waitcnt lgkmcnt(0)
	s_cmp_lg_u32 s98, 0
	s_cbranch_scc1 .Lhb_p5_0
	s_barrier
.Lhb_p5_0:
	s_setprio 1
	s_waitcnt lgkmcnt(0)
	v_mfma_scale_f32_16x16x128_f8f6f4 v[150:153], v[2:9], v[170:177], v[150:153], v182, v182 op_sel_hi:[0,0,0]
	v_mfma_scale_f32_16x16x128_f8f6f4 v[146:149], v[10:17], v[170:177], v[146:149], v182, v182 op_sel_hi:[0,0,0]
	v_mfma_scale_f32_16x16x128_f8f6f4 v[142:145], v[2:9], v[192:199], v[142:145], v182, v182 op_sel_hi:[0,0,0]
	v_mfma_scale_f32_16x16x128_f8f6f4 v[138:141], v[10:17], v[192:199], v[138:141], v182, v182 op_sel_hi:[0,0,0]
	v_mfma_scale_f32_16x16x128_f8f6f4 v[134:137], v[2:9], v[200:207], v[134:137], v182, v182 op_sel_hi:[0,0,0]
	v_mfma_scale_f32_16x16x128_f8f6f4 v[130:133], v[10:17], v[200:207], v[130:133], v182, v182 op_sel_hi:[0,0,0]
	v_mfma_scale_f32_16x16x128_f8f6f4 v[126:129], v[2:9], v[208:215], v[126:129], v182, v182 op_sel_hi:[0,0,0]
	v_mfma_scale_f32_16x16x128_f8f6f4 v[122:125], v[10:17], v[208:215], v[122:125], v182, v182 op_sel_hi:[0,0,0]
	s_setprio 0
	s_setprio 1
	v_mfma_scale_f32_16x16x128_f8f6f4 v[118:121], v[18:25], v[170:177], v[118:121], v182, v182 op_sel_hi:[0,0,0]
	v_mfma_scale_f32_16x16x128_f8f6f4 v[114:117], v[184:191], v[170:177], v[114:117], v182, v182 op_sel_hi:[0,0,0]
	v_mfma_scale_f32_16x16x128_f8f6f4 v[110:113], v[18:25], v[192:199], v[110:113], v182, v182 op_sel_hi:[0,0,0]
	v_mfma_scale_f32_16x16x128_f8f6f4 v[106:109], v[184:191], v[192:199], v[106:109], v182, v182 op_sel_hi:[0,0,0]
	v_mfma_scale_f32_16x16x128_f8f6f4 v[102:105], v[18:25], v[200:207], v[102:105], v182, v182 op_sel_hi:[0,0,0]
	v_mfma_scale_f32_16x16x128_f8f6f4 v[98:101], v[184:191], v[200:207], v[98:101], v182, v182 op_sel_hi:[0,0,0]
	v_mfma_scale_f32_16x16x128_f8f6f4 v[94:97], v[18:25], v[208:215], v[94:97], v182, v182 op_sel_hi:[0,0,0]
	v_mfma_scale_f32_16x16x128_f8f6f4 v[90:93], v[184:191], v[208:215], v[90:93], v182, v182 op_sel_hi:[0,0,0]
	s_setprio 0
	s_cmp_lg_u32 s98, 1
	s_cbranch_scc1 .Lhb_p5_1
	s_barrier
.Lhb_p5_1:
	s_add_i32 s50, s48, s29
	v_lshl_add_u64 v[170:171], s[24:25], 0, v[156:157]
	s_mov_b32 m0, s50
	ds_read_b128 v[192:195], v181 offset:16384
	ds_read_b128 v[196:199], v181 offset:17408
	ds_read_b128 v[200:203], v181 offset:18432
	ds_read_b128 v[204:207], v181 offset:19456
	ds_read_b128 v[208:211], v181 offset:20480
	ds_read_b128 v[212:215], v181 offset:21504
	ds_read_b128 v[216:219], v181 offset:22528
	ds_read_b128 v[220:223], v181 offset:23552
	global_load_lds_dwordx4 v[170:171], off
	s_add_i32 m0, s50, 0x2000
	s_add_u32 s70, s24, 0x40000
	v_lshl_add_u64 v[172:173], s[24:25], 0, v[160:161]
	s_addc_u32 s71, s25, 0
	s_add_i32 s50, s49, s29
	global_load_lds_dwordx4 v[172:173], off
	v_lshl_add_u64 v[174:175], s[70:71], 0, v[156:157]
	s_mov_b32 m0, s50
	v_lshl_add_u64 v[176:177], s[26:27], 0, v[158:159]
	global_load_lds_dwordx4 v[174:175], off
	v_lshl_add_u64 v[174:175], s[70:71], 0, v[160:161]
	s_add_i32 m0, s50, 0x2000
	s_nop 0
	global_load_lds_dwordx4 v[174:175], off
	v_lshl_add_u64 v[174:175], s[26:27], 0, v[154:155]
	s_mov_b32 m0, s17
	s_nop 0
	global_load_lds_dwordx4 v[174:175], off
	s_mov_b32 m0, s39
	s_nop 0
	global_load_lds_dwordx4 v[176:177], off
	s_waitcnt vmcnt(8)
	s_waitcnt lgkmcnt(0)
	s_cmp_lg_u32 s98, 0
	s_cbranch_scc1 .Lhb_p5_2
	s_barrier

.Lhb_p5_3:
	s_add_i32 s70, 0, 0x18000
	s_add_i32 s50, 0, 0x1c000
	v_add_u32_e32 v2, s70, v178
	v_add_u32_e32 v22, s50, v178
	ds_read_b128 v[10:13], v2
	ds_read_b128 v[14:17], v2 offset:1024
	ds_read_b128 v[184:187], v2 offset:2048
	ds_read_b128 v[188:191], v2 offset:3072
	ds_read_b128 v[2:5], v22
	ds_read_b128 v[6:9], v22 offset:1024
	ds_read_b128 v[18:21], v22 offset:2048
	ds_read_b128 v[22:25], v22 offset:3072
	s_add_u32 s26, s26, 0x40000
	s_addc_u32 s27, s27, 0
	s_mov_b32 m0, s40
	v_lshl_add_u64 v[224:225], s[26:27], 0, v[154:155]
	ds_read_b128 v[192:195], v181 offset:32768
	ds_read_b128 v[196:199], v181 offset:33792
	ds_read_b128 v[200:203], v181 offset:34816
	ds_read_b128 v[204:207], v181 offset:35840
	ds_read_b128 v[208:211], v181 offset:36864
	ds_read_b128 v[212:215], v181 offset:37888
	ds_read_b128 v[216:219], v181 offset:38912
	ds_read_b128 v[220:223], v181 offset:39936
	global_load_lds_dwordx4 v[224:225], off
	v_lshl_add_u64 v[224:225], s[26:27], 0, v[158:159]
	s_mov_b32 m0, s41
	s_nop 0
	global_load_lds_dwordx4 v[224:225], off
	s_waitcnt vmcnt(8)
	s_waitcnt lgkmcnt(0)
	s_cmp_lg_u32 s98, 0
	s_cbranch_scc1 .Lhb_p5_4
	s_barrier

.Lhb_p5_5:
	s_add_i32 s26, s70, s29
	v_lshl_add_u64 v[170:171], v[170:171], 0, s[8:9]
	s_mov_b32 m0, s26
	ds_read_b128 v[192:195], v181 offset:49152
	ds_read_b128 v[196:199], v181 offset:50176
	ds_read_b128 v[200:203], v181 offset:51200
	ds_read_b128 v[204:207], v181 offset:52224
	ds_read_b128 v[208:211], v181 offset:53248
	ds_read_b128 v[212:215], v181 offset:54272
	ds_read_b128 v[216:219], v181 offset:55296
	ds_read_b128 v[220:223], v181 offset:56320
	global_load_lds_dwordx4 v[170:171], off
	s_add_i32 m0, s26, 0x2000
	s_add_u32 s24, s24, 0x40080
	v_lshl_add_u64 v[170:171], v[172:173], 0, s[8:9]
	s_addc_u32 s25, s25, 0
	s_add_i32 s26, s50, s29
	global_load_lds_dwordx4 v[170:171], off
	v_lshl_add_u64 v[170:171], s[24:25], 0, v[156:157]
	s_mov_b32 m0, s26
	s_nop 0
	global_load_lds_dwordx4 v[170:171], off
	v_lshl_add_u64 v[170:171], s[24:25], 0, v[160:161]
	s_add_i32 m0, s26, 0x2000
	s_nop 0
	global_load_lds_dwordx4 v[170:171], off
	v_lshl_add_u64 v[170:171], v[174:175], 0, s[8:9]
	s_mov_b32 m0, s43
	s_nop 0
	global_load_lds_dwordx4 v[170:171], off
	v_lshl_add_u64 v[170:171], v[176:177], 0, s[8:9]
	s_mov_b32 m0, s44
	s_nop 0
	global_load_lds_dwordx4 v[170:171], off
	s_waitcnt vmcnt(8)
	s_waitcnt lgkmcnt(0)
	s_cmp_lg_u32 s98, 0
	s_cbranch_scc1 .Lhb_p5_6
	s_barrier

.Lhb_p5_7:
	s_add_u32 s22, s22, 0x100
	s_addc_u32 s23, s23, 0
	s_add_u32 s15, s15, 0x100
	s_addc_u32 s68, s68, 0
	s_cmp_ge_i32 s69, s62
	s_mov_b32 s24, s69
	s_cbranch_scc0 .LBB0_603

.LBB0_606:
	s_lshl_b32 s13, s16, 8
	v_add_u32_e32 v2, s13, v1
	v_add_u32_e32 v4, s13, v179
	v_ashrrev_i32_e32 v3, 31, v2
	v_ashrrev_i32_e32 v5, 31, v4
	v_lshlrev_b64 v[2:3], 12, v[2:3]
	s_cmp_eq_u32 s66, 0
	v_lshlrev_b64 v[4:5], 12, v[4:5]
	v_lshl_add_u64 v[2:3], s[4:5], 0, v[2:3]
	v_lshl_add_u64 v[4:5], s[6:7], 0, v[4:5]
	s_cselect_b64 vcc, -1, 0
	v_cndmask_b32_e32 v2, v4, v2, vcc
	v_lshl_or_b32 v4, s67, 8, v180
	v_cndmask_b32_e32 v3, v5, v3, vcc
	v_ashrrev_i32_e32 v5, 31, v4
	v_lshl_add_u64 v[6:7], v[4:5], 1, v[2:3]
	v_cvt_pk_bf16_f32 v2, v150, v151
	v_cvt_pk_bf16_f32 v3, v152, v153
	v_cvt_pk_bf16_f32 v4, v146, v147
	v_cvt_pk_bf16_f32 v5, v148, v149
	s_nop 15
	s_nop 15
	global_store_dwordx4 v[6:7], v[2:5], off
	v_add_co_u32_e32 v8, vcc, s42, v6
	s_nop 0
	v_cvt_pk_bf16_f32 v2, v118, v119
	v_cvt_pk_bf16_f32 v3, v120, v121
	v_cvt_pk_bf16_f32 v4, v114, v115
	v_cvt_pk_bf16_f32 v5, v116, v117
	global_store_dwordx4 v[6:7], v[2:5], off offset:256
	v_addc_co_u32_e32 v9, vcc, 0, v7, vcc
	s_nop 0
	v_cvt_pk_bf16_f32 v2, v142, v143
	v_cvt_pk_bf16_f32 v3, v144, v145
	v_cvt_pk_bf16_f32 v4, v138, v139
	v_cvt_pk_bf16_f32 v5, v140, v141
	global_store_dwordx4 v[8:9], v[2:5], off
	s_nop 1
	v_cvt_pk_bf16_f32 v2, v110, v111
	v_cvt_pk_bf16_f32 v3, v112, v113
	v_cvt_pk_bf16_f32 v4, v106, v107
	v_cvt_pk_bf16_f32 v5, v108, v109
	global_store_dwordx4 v[8:9], v[2:5], off offset:256
	v_add_co_u32_e32 v8, vcc, s56, v6
	s_nop 0
	v_cvt_pk_bf16_f32 v2, v134, v135
	v_cvt_pk_bf16_f32 v3, v136, v137
	v_cvt_pk_bf16_f32 v4, v130, v131
	v_cvt_pk_bf16_f32 v5, v132, v133
	v_addc_co_u32_e32 v9, vcc, 0, v7, vcc
	global_store_dwordx4 v[8:9], v[2:5], off
	s_nop 1
	v_cvt_pk_bf16_f32 v2, v102, v103
	v_cvt_pk_bf16_f32 v3, v104, v105
	v_cvt_pk_bf16_f32 v4, v98, v99
	v_cvt_pk_bf16_f32 v5, v100, v101
	global_store_dwordx4 v[8:9], v[2:5], off offset:256
	v_add_co_u32_e32 v8, vcc, s57, v6
	s_nop 0
	v_cvt_pk_bf16_f32 v2, v126, v127
	v_cvt_pk_bf16_f32 v3, v128, v129
	v_cvt_pk_bf16_f32 v4, v122, v123
	v_cvt_pk_bf16_f32 v5, v124, v125
	v_addc_co_u32_e32 v9, vcc, 0, v7, vcc
	global_store_dwordx4 v[8:9], v[2:5], off
	s_nop 1
	v_cvt_pk_bf16_f32 v2, v94, v95
	v_cvt_pk_bf16_f32 v3, v96, v97
	v_cvt_pk_bf16_f32 v4, v90, v91
	v_cvt_pk_bf16_f32 v5, v92, v93
	global_store_dwordx4 v[8:9], v[2:5], off offset:256
	v_add_co_u32_e32 v8, vcc, s58, v6
	s_nop 0
	v_cvt_pk_bf16_f32 v2, v86, v87
	v_cvt_pk_bf16_f32 v3, v88, v89
	v_cvt_pk_bf16_f32 v4, v82, v83
	v_cvt_pk_bf16_f32 v5, v84, v85
	v_addc_co_u32_e32 v9, vcc, 0, v7, vcc
	global_store_dwordx4 v[8:9], v[2:5], off
	s_nop 1
	v_cvt_pk_bf16_f32 v2, v54, v55
	v_cvt_pk_bf16_f32 v3, v56, v57
	v_cvt_pk_bf16_f32 v4, v50, v51
	v_cvt_pk_bf16_f32 v5, v52, v53
	global_store_dwordx4 v[8:9], v[2:5], off offset:256
	v_add_co_u32_e32 v8, vcc, s59, v6
	s_nop 0
	v_cvt_pk_bf16_f32 v2, v78, v79
	v_cvt_pk_bf16_f32 v3, v80, v81
	v_cvt_pk_bf16_f32 v4, v74, v75
	v_cvt_pk_bf16_f32 v5, v76, v77
	v_addc_co_u32_e32 v9, vcc, 0, v7, vcc
	global_store_dwordx4 v[8:9], v[2:5], off
	s_nop 1
	v_cvt_pk_bf16_f32 v2, v46, v47
	v_cvt_pk_bf16_f32 v3, v48, v49
	v_cvt_pk_bf16_f32 v4, v42, v43
	v_cvt_pk_bf16_f32 v5, v44, v45
	global_store_dwordx4 v[8:9], v[2:5], off offset:256
	v_add_co_u32_e32 v8, vcc, s60, v6
	s_nop 0
	v_cvt_pk_bf16_f32 v2, v70, v71
	v_cvt_pk_bf16_f32 v3, v72, v73
	v_cvt_pk_bf16_f32 v4, v66, v67
	v_cvt_pk_bf16_f32 v5, v68, v69
	v_addc_co_u32_e32 v9, vcc, 0, v7, vcc
	global_store_dwordx4 v[8:9], v[2:5], off
	v_add_co_u32_e32 v6, vcc, s61, v6
	s_nop 0
	v_cvt_pk_bf16_f32 v2, v38, v39
	v_cvt_pk_bf16_f32 v3, v40, v41
	v_cvt_pk_bf16_f32 v4, v34, v35
	v_cvt_pk_bf16_f32 v5, v36, v37
	global_store_dwordx4 v[8:9], v[2:5], off offset:256
	v_addc_co_u32_e32 v7, vcc, 0, v7, vcc
	s_nop 0
	v_cvt_pk_bf16_f32 v2, v62, v63
	v_cvt_pk_bf16_f32 v3, v64, v65
	v_cvt_pk_bf16_f32 v4, v58, v59
	v_cvt_pk_bf16_f32 v5, v60, v61
	global_store_dwordx4 v[6:7], v[2:5], off
	s_and_b64 vcc, exec, s[2:3]
	s_mov_b64 s[2:3], -1
	v_cvt_pk_bf16_f32 v2, v30, v31
	v_cvt_pk_bf16_f32 v3, v32, v33
	v_cvt_pk_bf16_f32 v4, v26, v27
	v_cvt_pk_bf16_f32 v5, v28, v29
	global_store_dwordx4 v[6:7], v[2:5], off offset:256
	s_cbranch_vccnz .LBB0_585
	s_ashr_i32 s2, s64, 31
	s_lshr_b32 s2, s2, 25
	s_add_i32 s2, s64, s2
	s_ashr_i32 s2, s2, 7
	s_cmp_lg_u32 s64, 0
	s_cselect_b32 s62, s2, 16
	s_andn2_b64 vcc, exec, s[0:1]
	s_cbranch_vccnz .LBB0_584
	s_branch .LBB0_584

.LBB0_819:
	s_add_u32 s4, s74, 0x6c00000
	s_addc_u32 s5, s75, 0
	s_add_u32 s6, s74, 0xc00000
	s_addc_u32 s7, s75, 0
	s_lshl_b32 s8, s8, 5
	s_and_b32 s14, s8, 0x60
	s_mov_b64 s[8:9], 0x80
	s_add_i32 m0, s17, 0x18000
	v_lshl_add_u64 v[8:9], v[8:9], 0, s[8:9]
	s_lshl_b32 s11, s3, 13
	s_lshl_b32 s15, s14, 7
	s_waitcnt vmcnt(2)
	v_readfirstlane_b32 s98, v0
	s_nop 3
	s_lshr_b32 s98, s98, 8
	s_barrier
	global_load_lds_dwordx4 v[8:9], off
	v_lshl_add_u64 v[6:7], v[6:7], 0, s[8:9]
	s_add_i32 m0, s17, 0x1a000
	s_add_i32 s43, s17, 0x8000
	s_add_i32 s44, s17, 0xa000
	global_load_lds_dwordx4 v[6:7], off
	v_lshl_add_u64 v[2:3], v[2:3], 0, s[8:9]
	s_mov_b32 m0, s43
	s_add_u32 s12, s24, 0x100080
	global_load_lds_dwordx4 v[2:3], off
	v_lshl_add_u64 v[2:3], v[4:5], 0, s[8:9]
	s_mov_b32 m0, s44
	s_addc_u32 s13, s25, 0
	global_load_lds_dwordx4 v[2:3], off
	s_add_i32 m0, s17, 0x1c000
	v_lshl_add_u64 v[2:3], s[12:13], 0, v[156:157]
	global_load_lds_dwordx4 v[2:3], off
	v_lshl_add_u64 v[2:3], s[12:13], 0, v[160:161]
	s_add_i32 m0, s17, 0x1e000
	s_sext_i32_i8 s63, s2
	global_load_lds_dwordx4 v[2:3], off
	v_and_b32_e32 v2, 15, v0
	v_lshlrev_b32_e32 v3, 1, v13
	v_lshlrev_b32_e32 v4, 2, v0
	v_lshlrev_b32_e32 v5, 6, v0
	s_movk_i32 s2, 0x3c0
	v_lshl_or_b32 v1, s3, 6, v2
	v_lshl_or_b32 v2, v2, 6, v3
	v_and_b32_e32 v4, 32, v4
	v_and_or_b32 v3, v5, s2, v3
	v_bitop3_b32 v178, s15, v3, v4 bitop3:0xf6
	v_lshlrev_b32_e32 v3, 10, v0
	v_bitop3_b32 v2, v2, s11, v4 bitop3:0xde
	v_and_b32_e32 v3, 0x60000, v3
	v_lshlrev_b32_e32 v4, 13, v12
	v_or3_b32 v3, v10, v3, v4
	v_add_u32_e32 v162, v3, v11
	v_lshlrev_b32_e32 v3, 6, v14
	s_waitcnt vmcnt(6)
	v_and_b32_e32 v3, 0xe0000, v3
	v_mov_b32_e32 v28, v157
	v_mov_b32_e32 v29, v157
	s_cmpk_lt_u32 s10, 0x100
	v_or3_b32 v3, v10, v3, v4
	v_mov_b32_e32 v26, v157
	v_mov_b32_e32 v27, v157
	v_mov_b64_e32 v[32:33], v[28:29]
	v_mov_b64_e32 v[36:37], v[28:29]
	v_mov_b64_e32 v[40:41], v[28:29]
	v_mov_b64_e32 v[44:45], v[28:29]
	v_mov_b64_e32 v[48:49], v[28:29]
	v_mov_b64_e32 v[52:53], v[28:29]
	v_mov_b64_e32 v[56:57], v[28:29]
	v_mov_b64_e32 v[60:61], v[28:29]
	v_mov_b64_e32 v[64:65], v[28:29]
	v_mov_b64_e32 v[68:69], v[28:29]
	v_mov_b64_e32 v[72:73], v[28:29]
	v_mov_b64_e32 v[76:77], v[28:29]
	v_mov_b64_e32 v[80:81], v[28:29]
	v_mov_b64_e32 v[84:85], v[28:29]
	v_mov_b64_e32 v[88:89], v[28:29]
	v_mov_b64_e32 v[92:93], v[28:29]
	v_mov_b64_e32 v[96:97], v[28:29]
	v_mov_b64_e32 v[100:101], v[28:29]
	v_mov_b64_e32 v[104:105], v[28:29]
	v_mov_b64_e32 v[108:109], v[28:29]
	v_mov_b64_e32 v[112:113], v[28:29]
	v_mov_b64_e32 v[116:117], v[28:29]
	v_mov_b64_e32 v[120:121], v[28:29]
	v_mov_b64_e32 v[124:125], v[28:29]
	v_mov_b64_e32 v[128:129], v[28:29]
	v_mov_b64_e32 v[132:133], v[28:29]
	v_mov_b64_e32 v[136:137], v[28:29]
	v_mov_b64_e32 v[140:141], v[28:29]
	v_mov_b64_e32 v[144:145], v[28:29]
	v_mov_b64_e32 v[148:149], v[28:29]
	v_mov_b64_e32 v[152:153], v[28:29]
	s_cselect_b64 s[10:11], -1, 0
	s_ashr_i32 s45, s33, 31
	s_ashr_i32 s46, s30, 31
	v_add_u32_e32 v179, 0xffffc000, v1
	v_or_b32_e32 v180, s14, v13
	v_mov_b32_e32 v163, v157
	v_add_u32_e32 v164, v3, v11
	v_mov_b32_e32 v165, v157
	s_mov_b32 s47, 0
	s_add_i32 s48, 0, 0x10000
	s_add_i32 s49, 0, 0x14000
	v_add_u32_e32 v181, 0, v2
	v_mov_b32_e32 v182, 0x7c7c7c7c
	s_mov_b32 s52, 0x20000
	s_mov_b32 s53, 0x30000
	s_mov_b32 s54, 0x80000
	s_mov_b32 s55, 0x90000
	s_mov_b32 s56, 0xa0000
	s_mov_b32 s57, 0xb0000
	v_mov_b64_e32 v[166:167], 0xff
	v_mov_b64_e32 v[168:169], 0x1ff
	v_mov_b64_e32 v[30:31], v[26:27]
	v_mov_b64_e32 v[34:35], v[26:27]
	v_mov_b64_e32 v[38:39], v[26:27]
	v_mov_b64_e32 v[42:43], v[26:27]
	v_mov_b64_e32 v[46:47], v[26:27]
	v_mov_b64_e32 v[50:51], v[26:27]
	v_mov_b64_e32 v[54:55], v[26:27]
	v_mov_b64_e32 v[58:59], v[26:27]
	v_mov_b64_e32 v[62:63], v[26:27]
	v_mov_b64_e32 v[66:67], v[26:27]
	v_mov_b64_e32 v[70:71], v[26:27]
	v_mov_b64_e32 v[74:75], v[26:27]
	v_mov_b64_e32 v[78:79], v[26:27]
	v_mov_b64_e32 v[82:83], v[26:27]
	v_mov_b64_e32 v[86:87], v[26:27]
	v_mov_b64_e32 v[90:91], v[26:27]
	v_mov_b64_e32 v[94:95], v[26:27]
	v_mov_b64_e32 v[98:99], v[26:27]
	v_mov_b64_e32 v[102:103], v[26:27]
	v_mov_b64_e32 v[106:107], v[26:27]
	v_mov_b64_e32 v[110:111], v[26:27]
	v_mov_b64_e32 v[114:115], v[26:27]
	v_mov_b64_e32 v[118:119], v[26:27]
	v_mov_b64_e32 v[122:123], v[26:27]
	v_mov_b64_e32 v[126:127], v[26:27]
	v_mov_b64_e32 v[130:131], v[26:27]
	v_mov_b64_e32 v[134:135], v[26:27]
	v_mov_b64_e32 v[138:139], v[26:27]
	v_mov_b64_e32 v[142:143], v[26:27]
	v_mov_b64_e32 v[146:147], v[26:27]
	v_mov_b64_e32 v[150:151], v[26:27]
	s_barrier
	s_branch .LBB0_822

.LBB0_839:
	v_add_u32_e32 v14, s48, v178
	v_add_u32_e32 v170, s49, v178
	ds_read_b128 v[2:5], v14
	ds_read_b128 v[6:9], v14 offset:1024
	ds_read_b128 v[10:13], v14 offset:2048
	ds_read_b128 v[14:17], v14 offset:3072
	ds_read_b128 v[18:21], v170
	ds_read_b128 v[22:25], v170 offset:1024
	ds_read_b128 v[184:187], v170 offset:2048
	ds_read_b128 v[188:191], v170 offset:3072
	s_add_i32 s65, s24, 2
	s_add_u32 s25, s22, 0xfff00080
	s_addc_u32 s26, s23, -1
	s_cmp_eq_u32 s13, s24
	s_cselect_b32 s24, s20, s15
	s_cselect_b32 s27, s19, s26
	s_cselect_b32 s26, s18, s25
	s_cselect_b32 s25, s21, s64
	v_lshl_add_u64 v[216:217], s[22:23], 0, v[162:163]
	s_add_i32 m0, s17, 0xc000
	ds_read_b128 v[170:173], v181
	ds_read_b128 v[174:177], v181 offset:1024
	ds_read_b128 v[192:195], v181 offset:2048
	ds_read_b128 v[196:199], v181 offset:3072
	ds_read_b128 v[200:203], v181 offset:4096
	ds_read_b128 v[204:207], v181 offset:5120
	ds_read_b128 v[208:211], v181 offset:6144
	ds_read_b128 v[212:215], v181 offset:7168
	global_load_lds_dwordx4 v[216:217], off
	v_lshl_add_u64 v[216:217], s[22:23], 0, v[164:165]
	s_add_i32 m0, s17, 0xe000
	s_nop 0
	global_load_lds_dwordx4 v[216:217], off
	s_waitcnt vmcnt(8)
	s_waitcnt lgkmcnt(0)
	s_cmp_lg_u32 s98, 0
	s_cbranch_scc1 .Lhb_p8_0
	s_barrier

.Lhb_p8_1:
	s_add_i32 s50, s48, s29
	v_lshl_add_u64 v[170:171], s[24:25], 0, v[156:157]
	s_mov_b32 m0, s50
	ds_read_b128 v[192:195], v181 offset:16384
	ds_read_b128 v[196:199], v181 offset:17408
	ds_read_b128 v[200:203], v181 offset:18432
	ds_read_b128 v[204:207], v181 offset:19456
	ds_read_b128 v[208:211], v181 offset:20480
	ds_read_b128 v[212:215], v181 offset:21504
	ds_read_b128 v[216:219], v181 offset:22528
	ds_read_b128 v[220:223], v181 offset:23552
	global_load_lds_dwordx4 v[170:171], off
	s_add_i32 m0, s50, 0x2000
	s_add_u32 s66, s24, 0x100000
	v_lshl_add_u64 v[172:173], s[24:25], 0, v[160:161]
	s_addc_u32 s67, s25, 0
	s_add_i32 s50, s49, s29
	global_load_lds_dwordx4 v[172:173], off
	v_lshl_add_u64 v[174:175], s[66:67], 0, v[156:157]
	s_mov_b32 m0, s50
	v_lshl_add_u64 v[176:177], s[26:27], 0, v[158:159]
	global_load_lds_dwordx4 v[174:175], off
	v_lshl_add_u64 v[174:175], s[66:67], 0, v[160:161]
	s_add_i32 m0, s50, 0x2000
	s_nop 0
	global_load_lds_dwordx4 v[174:175], off
	v_lshl_add_u64 v[174:175], s[26:27], 0, v[154:155]
	s_mov_b32 m0, s17
	s_nop 0
	global_load_lds_dwordx4 v[174:175], off
	s_mov_b32 m0, s39
	s_nop 0
	global_load_lds_dwordx4 v[176:177], off
	s_waitcnt vmcnt(8)
	s_waitcnt lgkmcnt(0)
	s_cmp_lg_u32 s98, 0
	s_cbranch_scc1 .Lhb_p8_2
	s_barrier

.Lhb_p8_3:
	s_add_i32 s66, 0, 0x18000
	s_add_i32 s50, 0, 0x1c000
	v_add_u32_e32 v2, s66, v178
	v_add_u32_e32 v22, s50, v178
	ds_read_b128 v[10:13], v2
	ds_read_b128 v[14:17], v2 offset:1024
	ds_read_b128 v[184:187], v2 offset:2048
	ds_read_b128 v[188:191], v2 offset:3072
	ds_read_b128 v[2:5], v22
	ds_read_b128 v[6:9], v22 offset:1024
	ds_read_b128 v[18:21], v22 offset:2048
	ds_read_b128 v[22:25], v22 offset:3072
	s_add_u32 s26, s26, 0x100000
	s_addc_u32 s27, s27, 0
	s_mov_b32 m0, s40
	v_lshl_add_u64 v[224:225], s[26:27], 0, v[154:155]
	ds_read_b128 v[192:195], v181 offset:32768
	ds_read_b128 v[196:199], v181 offset:33792
	ds_read_b128 v[200:203], v181 offset:34816
	ds_read_b128 v[204:207], v181 offset:35840
	ds_read_b128 v[208:211], v181 offset:36864
	ds_read_b128 v[212:215], v181 offset:37888
	ds_read_b128 v[216:219], v181 offset:38912
	ds_read_b128 v[220:223], v181 offset:39936
	global_load_lds_dwordx4 v[224:225], off
	v_lshl_add_u64 v[224:225], s[26:27], 0, v[158:159]
	s_mov_b32 m0, s41
	s_nop 0
	global_load_lds_dwordx4 v[224:225], off
	s_waitcnt vmcnt(8)
	s_waitcnt lgkmcnt(0)
	s_cmp_lg_u32 s98, 0
	s_cbranch_scc1 .Lhb_p8_4
	s_barrier

.Lhb_p8_5:
	s_add_i32 s26, s66, s29
	v_lshl_add_u64 v[170:171], v[170:171], 0, s[8:9]
	s_mov_b32 m0, s26
	ds_read_b128 v[192:195], v181 offset:49152
	ds_read_b128 v[196:199], v181 offset:50176
	ds_read_b128 v[200:203], v181 offset:51200
	ds_read_b128 v[204:207], v181 offset:52224
	ds_read_b128 v[208:211], v181 offset:53248
	ds_read_b128 v[212:215], v181 offset:54272
	ds_read_b128 v[216:219], v181 offset:55296
	ds_read_b128 v[220:223], v181 offset:56320
	global_load_lds_dwordx4 v[170:171], off
	s_add_i32 m0, s26, 0x2000
	s_add_u32 s24, s24, 0x100080
	v_lshl_add_u64 v[170:171], v[172:173], 0, s[8:9]
	s_addc_u32 s25, s25, 0
	s_add_i32 s26, s50, s29
	global_load_lds_dwordx4 v[170:171], off
	v_lshl_add_u64 v[170:171], s[24:25], 0, v[156:157]
	s_mov_b32 m0, s26
	s_nop 0
	global_load_lds_dwordx4 v[170:171], off
	v_lshl_add_u64 v[170:171], s[24:25], 0, v[160:161]
	s_add_i32 m0, s26, 0x2000
	s_nop 0
	global_load_lds_dwordx4 v[170:171], off
	v_lshl_add_u64 v[170:171], v[174:175], 0, s[8:9]
	s_mov_b32 m0, s43
	s_nop 0
	global_load_lds_dwordx4 v[170:171], off
	v_lshl_add_u64 v[170:171], v[176:177], 0, s[8:9]
	s_mov_b32 m0, s44
	s_nop 0
	global_load_lds_dwordx4 v[170:171], off
	s_waitcnt vmcnt(8)
	s_waitcnt lgkmcnt(0)
	s_cmp_lg_u32 s98, 0
	s_cbranch_scc1 .Lhb_p8_6
	s_barrier

.Lhb_p8_7:
	s_add_u32 s22, s22, 0x100
	s_addc_u32 s23, s23, 0
	s_add_u32 s15, s15, 0x100
	s_addc_u32 s64, s64, 0
	s_cmp_ge_i32 s65, s58
	s_mov_b32 s24, s65
	s_cbranch_scc0 .LBB0_839

.LBB0_842:
	s_lshl_b32 s13, s16, 8
	v_add_u32_e32 v2, s13, v1
	v_add_u32_e32 v4, s13, v179
	v_ashrrev_i32_e32 v3, 31, v2
	v_ashrrev_i32_e32 v5, 31, v4
	v_lshlrev_b64 v[2:3], 12, v[2:3]
	s_cmp_eq_u32 s62, 0
	v_lshlrev_b64 v[4:5], 12, v[4:5]
	v_lshl_add_u64 v[2:3], s[4:5], 0, v[2:3]
	v_lshl_add_u64 v[4:5], s[6:7], 0, v[4:5]
	s_cselect_b64 vcc, -1, 0
	v_cndmask_b32_e32 v2, v4, v2, vcc
	v_lshl_or_b32 v4, s63, 8, v180
	v_cndmask_b32_e32 v3, v5, v3, vcc
	v_ashrrev_i32_e32 v5, 31, v4
	v_lshl_add_u64 v[6:7], v[4:5], 1, v[2:3]
	v_cvt_pk_bf16_f32 v2, v150, v151
	v_cvt_pk_bf16_f32 v3, v152, v153
	v_cvt_pk_bf16_f32 v4, v146, v147
	v_cvt_pk_bf16_f32 v5, v148, v149
	s_nop 15
	s_nop 15
	global_store_dwordx4 v[6:7], v[2:5], off
	v_add_co_u32_e32 v8, vcc, s42, v6
	s_nop 0
	v_cvt_pk_bf16_f32 v2, v118, v119
	v_cvt_pk_bf16_f32 v3, v120, v121
	v_cvt_pk_bf16_f32 v4, v114, v115
	v_cvt_pk_bf16_f32 v5, v116, v117
	global_store_dwordx4 v[6:7], v[2:5], off offset:256
	v_addc_co_u32_e32 v9, vcc, 0, v7, vcc
	s_nop 0
	v_cvt_pk_bf16_f32 v2, v142, v143
	v_cvt_pk_bf16_f32 v3, v144, v145
	v_cvt_pk_bf16_f32 v4, v138, v139
	v_cvt_pk_bf16_f32 v5, v140, v141
	global_store_dwordx4 v[8:9], v[2:5], off
	s_nop 1
	v_cvt_pk_bf16_f32 v2, v110, v111
	v_cvt_pk_bf16_f32 v3, v112, v113
	v_cvt_pk_bf16_f32 v4, v106, v107
	v_cvt_pk_bf16_f32 v5, v108, v109
	global_store_dwordx4 v[8:9], v[2:5], off offset:256
	v_add_co_u32_e32 v8, vcc, s52, v6
	s_nop 0
	v_cvt_pk_bf16_f32 v2, v134, v135
	v_cvt_pk_bf16_f32 v3, v136, v137
	v_cvt_pk_bf16_f32 v4, v130, v131
	v_cvt_pk_bf16_f32 v5, v132, v133
	v_addc_co_u32_e32 v9, vcc, 0, v7, vcc
	global_store_dwordx4 v[8:9], v[2:5], off
	s_nop 1
	v_cvt_pk_bf16_f32 v2, v102, v103
	v_cvt_pk_bf16_f32 v3, v104, v105
	v_cvt_pk_bf16_f32 v4, v98, v99
	v_cvt_pk_bf16_f32 v5, v100, v101
	global_store_dwordx4 v[8:9], v[2:5], off offset:256
	v_add_co_u32_e32 v8, vcc, s53, v6
	s_nop 0
	v_cvt_pk_bf16_f32 v2, v126, v127
	v_cvt_pk_bf16_f32 v3, v128, v129
	v_cvt_pk_bf16_f32 v4, v122, v123
	v_cvt_pk_bf16_f32 v5, v124, v125
	v_addc_co_u32_e32 v9, vcc, 0, v7, vcc
	global_store_dwordx4 v[8:9], v[2:5], off
	s_nop 1
	v_cvt_pk_bf16_f32 v2, v94, v95
	v_cvt_pk_bf16_f32 v3, v96, v97
	v_cvt_pk_bf16_f32 v4, v90, v91
	v_cvt_pk_bf16_f32 v5, v92, v93
	global_store_dwordx4 v[8:9], v[2:5], off offset:256
	v_add_co_u32_e32 v8, vcc, s54, v6
	s_nop 0
	v_cvt_pk_bf16_f32 v2, v86, v87
	v_cvt_pk_bf16_f32 v3, v88, v89
	v_cvt_pk_bf16_f32 v4, v82, v83
	v_cvt_pk_bf16_f32 v5, v84, v85
	v_addc_co_u32_e32 v9, vcc, 0, v7, vcc
	global_store_dwordx4 v[8:9], v[2:5], off
	s_nop 1
	v_cvt_pk_bf16_f32 v2, v54, v55
	v_cvt_pk_bf16_f32 v3, v56, v57
	v_cvt_pk_bf16_f32 v4, v50, v51
	v_cvt_pk_bf16_f32 v5, v52, v53
	global_store_dwordx4 v[8:9], v[2:5], off offset:256
	v_add_co_u32_e32 v8, vcc, s55, v6
	s_nop 0
	v_cvt_pk_bf16_f32 v2, v78, v79
	v_cvt_pk_bf16_f32 v3, v80, v81
	v_cvt_pk_bf16_f32 v4, v74, v75
	v_cvt_pk_bf16_f32 v5, v76, v77
	v_addc_co_u32_e32 v9, vcc, 0, v7, vcc
	global_store_dwordx4 v[8:9], v[2:5], off
	s_nop 1
	v_cvt_pk_bf16_f32 v2, v46, v47
	v_cvt_pk_bf16_f32 v3, v48, v49
	v_cvt_pk_bf16_f32 v4, v42, v43
	v_cvt_pk_bf16_f32 v5, v44, v45
	global_store_dwordx4 v[8:9], v[2:5], off offset:256
	v_add_co_u32_e32 v8, vcc, s56, v6
	s_nop 0
	v_cvt_pk_bf16_f32 v2, v70, v71
	v_cvt_pk_bf16_f32 v3, v72, v73
	v_cvt_pk_bf16_f32 v4, v66, v67
	v_cvt_pk_bf16_f32 v5, v68, v69
	v_addc_co_u32_e32 v9, vcc, 0, v7, vcc
	global_store_dwordx4 v[8:9], v[2:5], off
	v_add_co_u32_e32 v6, vcc, s57, v6
	s_nop 0
	v_cvt_pk_bf16_f32 v2, v38, v39
	v_cvt_pk_bf16_f32 v3, v40, v41
	v_cvt_pk_bf16_f32 v4, v34, v35
	v_cvt_pk_bf16_f32 v5, v36, v37
	global_store_dwordx4 v[8:9], v[2:5], off offset:256
	v_addc_co_u32_e32 v7, vcc, 0, v7, vcc
	s_nop 0
	v_cvt_pk_bf16_f32 v2, v62, v63
	v_cvt_pk_bf16_f32 v3, v64, v65
	v_cvt_pk_bf16_f32 v4, v58, v59
	v_cvt_pk_bf16_f32 v5, v60, v61
	global_store_dwordx4 v[6:7], v[2:5], off
	s_and_b64 vcc, exec, s[2:3]
	s_mov_b64 s[2:3], -1
	v_cvt_pk_bf16_f32 v2, v30, v31
	v_cvt_pk_bf16_f32 v3, v32, v33
	v_cvt_pk_bf16_f32 v4, v26, v27
	v_cvt_pk_bf16_f32 v5, v28, v29
	global_store_dwordx4 v[6:7], v[2:5], off offset:256
	s_cbranch_vccnz .LBB0_821
	s_ashr_i32 s2, s60, 31
	s_lshr_b32 s2, s2, 25
	s_add_i32 s2, s60, s2
	s_ashr_i32 s2, s2, 7
	s_cmp_lg_u32 s60, 0
	s_cselect_b32 s58, s2, 64
	s_andn2_b64 vcc, exec, s[0:1]
	s_cbranch_vccnz .LBB0_820
	s_branch .LBB0_820
